# L2 GEMM epilogue stores made write-through (sc0 sc1) so the following grid barrier's L2 write-back has less to flush
# speedup vs baseline: 1.0069x; 1.0042x over previous
.Lg2_loop:
	s_add_u32 s54, s54, 0x80
	s_addc_u32 s55, s55, 0
	s_add_u32 s56, s56, 0x80
	s_addc_u32 s57, s57, 0
	ds_read_b128 v[64:67], v156
	ds_read_b128 v[68:71], v158 offset:16384
	ds_read_b128 v[80:83], v159 offset:16384
	ds_read_b128 v[72:75], v157
	ds_read_b128 v[76:79], v158 offset:18432
	ds_read_b128 v[92:95], v159 offset:18432
	ds_read_b128 v[84:87], v158 offset:20480
	ds_read_b128 v[116:119], v159 offset:20480
	ds_read_b128 v[88:91], v158 offset:22528
	ds_read_b128 v[120:123], v159 offset:22528
	s_waitcnt lgkmcnt(8)
	v_mfma_f32_16x16x32_bf16 v[36:39], v[64:67], v[68:71], v[36:39]
	s_waitcnt lgkmcnt(5)
	v_mfma_f32_16x16x32_bf16 v[32:35], v[64:67], v[76:79], v[32:35]
	s_waitcnt lgkmcnt(3)
	s_add_u32 m0, s58, 0x8000
	v_mfma_f32_16x16x32_bf16 v[28:31], v[64:67], v[84:87], v[28:31]
	global_load_lds_dwordx4 v152, s[54:55]
	s_waitcnt lgkmcnt(1)
	v_mfma_f32_16x16x32_bf16 v[24:27], v[64:67], v[88:91], v[24:27]
	ds_read_b128 v[64:67], v156 offset:2048
	ds_read_b128 v[124:127], v157 offset:2048
	s_waitcnt lgkmcnt(1)
	v_mfma_f32_16x16x32_bf16 v[8:11], v[64:67], v[68:71], v[8:11]
	s_add_u32 m0, m0, 0x400
	v_mfma_f32_16x16x32_bf16 v[4:7], v[64:67], v[76:79], v[4:7]
	global_load_lds_dwordx4 v153, s[54:55]
	v_mfma_f32_16x16x32_bf16 v[0:3], v[64:67], v[84:87], v[0:3]
	v_mfma_f32_16x16x32_bf16 v[20:23], v[64:67], v[88:91], v[20:23]
	ds_read_b128 v[64:67], v156 offset:4096
	ds_read_b128 v[128:131], v157 offset:4096
	s_waitcnt lgkmcnt(1)
	s_add_u32 m0, m0, 0x400
	v_mfma_f32_16x16x32_bf16 v[12:15], v[64:67], v[68:71], v[12:15]
	global_load_lds_dwordx4 v154, s[54:55]
	v_mfma_f32_16x16x32_bf16 v[16:19], v[64:67], v[76:79], v[16:19]
	v_mfma_f32_16x16x32_bf16 v[56:59], v[64:67], v[84:87], v[56:59]
	s_add_u32 m0, m0, 0x400
	v_mfma_f32_16x16x32_bf16 v[52:55], v[64:67], v[88:91], v[52:55]
	global_load_lds_dwordx4 v155, s[54:55]
	ds_read_b128 v[64:67], v156 offset:6144
	ds_read_b128 v[132:135], v157 offset:6144
	s_waitcnt lgkmcnt(1)
	v_mfma_f32_16x16x32_bf16 v[48:51], v[64:67], v[68:71], v[48:51]
	v_mfma_f32_16x16x32_bf16 v[44:47], v[64:67], v[76:79], v[44:47]
	s_add_u32 m0, m0, 0x3400
	v_mfma_f32_16x16x32_bf16 v[40:43], v[64:67], v[84:87], v[40:43]
	global_load_lds_dwordx4 v152, s[56:57]
	v_mfma_f32_16x16x32_bf16 v[60:63], v[64:67], v[88:91], v[60:63]
	v_mfma_f32_16x16x32_bf16 v[36:39], v[72:75], v[80:83], v[36:39]
	s_add_u32 m0, m0, 0x400
	v_mfma_f32_16x16x32_bf16 v[32:35], v[72:75], v[92:95], v[32:35]
	global_load_lds_dwordx4 v153, s[56:57]
	v_mfma_f32_16x16x32_bf16 v[28:31], v[72:75], v[116:119], v[28:31]
	v_mfma_f32_16x16x32_bf16 v[24:27], v[72:75], v[120:123], v[24:27]
	s_add_u32 m0, m0, 0x400
	v_mfma_f32_16x16x32_bf16 v[8:11], v[124:127], v[80:83], v[8:11]
	global_load_lds_dwordx4 v154, s[56:57]
	v_mfma_f32_16x16x32_bf16 v[4:7], v[124:127], v[92:95], v[4:7]
	v_mfma_f32_16x16x32_bf16 v[0:3], v[124:127], v[116:119], v[0:3]
	s_add_u32 m0, m0, 0x400
	v_mfma_f32_16x16x32_bf16 v[20:23], v[124:127], v[120:123], v[20:23]
	global_load_lds_dwordx4 v155, s[56:57]
	v_mfma_f32_16x16x32_bf16 v[12:15], v[128:131], v[80:83], v[12:15]
	s_waitcnt lgkmcnt(0)
	v_mfma_f32_16x16x32_bf16 v[48:51], v[132:135], v[80:83], v[48:51]
	v_mfma_f32_16x16x32_bf16 v[16:19], v[128:131], v[92:95], v[16:19]
	v_mfma_f32_16x16x32_bf16 v[44:47], v[132:135], v[92:95], v[44:47]
	v_mfma_f32_16x16x32_bf16 v[56:59], v[128:131], v[116:119], v[56:59]
	v_mfma_f32_16x16x32_bf16 v[52:55], v[128:131], v[120:123], v[52:55]
	v_mfma_f32_16x16x32_bf16 v[40:43], v[132:135], v[116:119], v[40:43]
	v_mfma_f32_16x16x32_bf16 v[60:63], v[132:135], v[120:123], v[60:63]
	s_waitcnt vmcnt(0)
	s_barrier
	s_add_u32 s54, s54, 0x80
	s_addc_u32 s55, s55, 0
	s_add_u32 s56, s56, 0x80
	s_addc_u32 s57, s57, 0
	ds_read_b128 v[64:67], v156 offset:32768
	ds_read_b128 v[68:71], v158 offset:49152
	ds_read_b128 v[80:83], v159 offset:49152
	ds_read_b128 v[72:75], v157 offset:32768
	ds_read_b128 v[76:79], v158 offset:51200
	ds_read_b128 v[92:95], v159 offset:51200
	ds_read_b128 v[84:87], v158 offset:53248
	ds_read_b128 v[116:119], v159 offset:53248
	ds_read_b128 v[88:91], v158 offset:55296
	ds_read_b128 v[120:123], v159 offset:55296
	s_waitcnt lgkmcnt(8)
	v_mfma_f32_16x16x32_bf16 v[36:39], v[64:67], v[68:71], v[36:39]
	s_waitcnt lgkmcnt(5)
	v_mfma_f32_16x16x32_bf16 v[32:35], v[64:67], v[76:79], v[32:35]
	s_waitcnt lgkmcnt(3)
	s_add_u32 m0, s58, 0x0
	v_mfma_f32_16x16x32_bf16 v[28:31], v[64:67], v[84:87], v[28:31]
	global_load_lds_dwordx4 v152, s[54:55]
	s_waitcnt lgkmcnt(1)
	v_mfma_f32_16x16x32_bf16 v[24:27], v[64:67], v[88:91], v[24:27]
	ds_read_b128 v[64:67], v156 offset:34816
	ds_read_b128 v[124:127], v157 offset:34816
	s_waitcnt lgkmcnt(1)
	v_mfma_f32_16x16x32_bf16 v[8:11], v[64:67], v[68:71], v[8:11]
	s_add_u32 m0, m0, 0x400
	v_mfma_f32_16x16x32_bf16 v[4:7], v[64:67], v[76:79], v[4:7]
	global_load_lds_dwordx4 v153, s[54:55]
	v_mfma_f32_16x16x32_bf16 v[0:3], v[64:67], v[84:87], v[0:3]
	v_mfma_f32_16x16x32_bf16 v[20:23], v[64:67], v[88:91], v[20:23]
	ds_read_b128 v[64:67], v156 offset:36864
	ds_read_b128 v[128:131], v157 offset:36864
	s_waitcnt lgkmcnt(1)
	s_add_u32 m0, m0, 0x400
	v_mfma_f32_16x16x32_bf16 v[12:15], v[64:67], v[68:71], v[12:15]
	global_load_lds_dwordx4 v154, s[54:55]
	v_mfma_f32_16x16x32_bf16 v[16:19], v[64:67], v[76:79], v[16:19]
	v_mfma_f32_16x16x32_bf16 v[56:59], v[64:67], v[84:87], v[56:59]
	s_add_u32 m0, m0, 0x400
	v_mfma_f32_16x16x32_bf16 v[52:55], v[64:67], v[88:91], v[52:55]
	global_load_lds_dwordx4 v155, s[54:55]
	ds_read_b128 v[64:67], v156 offset:38912
	ds_read_b128 v[132:135], v157 offset:38912
	s_waitcnt lgkmcnt(1)
	v_mfma_f32_16x16x32_bf16 v[48:51], v[64:67], v[68:71], v[48:51]
	v_mfma_f32_16x16x32_bf16 v[44:47], v[64:67], v[76:79], v[44:47]
	s_add_u32 m0, m0, 0x3400
	v_mfma_f32_16x16x32_bf16 v[40:43], v[64:67], v[84:87], v[40:43]
	global_load_lds_dwordx4 v152, s[56:57]
	v_mfma_f32_16x16x32_bf16 v[60:63], v[64:67], v[88:91], v[60:63]
	v_mfma_f32_16x16x32_bf16 v[36:39], v[72:75], v[80:83], v[36:39]
	s_add_u32 m0, m0, 0x400
	v_mfma_f32_16x16x32_bf16 v[32:35], v[72:75], v[92:95], v[32:35]
	global_load_lds_dwordx4 v153, s[56:57]
	v_mfma_f32_16x16x32_bf16 v[28:31], v[72:75], v[116:119], v[28:31]
	v_mfma_f32_16x16x32_bf16 v[24:27], v[72:75], v[120:123], v[24:27]
	s_add_u32 m0, m0, 0x400
	v_mfma_f32_16x16x32_bf16 v[8:11], v[124:127], v[80:83], v[8:11]
	global_load_lds_dwordx4 v154, s[56:57]
	v_mfma_f32_16x16x32_bf16 v[4:7], v[124:127], v[92:95], v[4:7]
	v_mfma_f32_16x16x32_bf16 v[0:3], v[124:127], v[116:119], v[0:3]
	s_add_u32 m0, m0, 0x400
	v_mfma_f32_16x16x32_bf16 v[20:23], v[124:127], v[120:123], v[20:23]
	global_load_lds_dwordx4 v155, s[56:57]
	v_mfma_f32_16x16x32_bf16 v[12:15], v[128:131], v[80:83], v[12:15]
	s_waitcnt lgkmcnt(0)
	v_mfma_f32_16x16x32_bf16 v[48:51], v[132:135], v[80:83], v[48:51]
	v_mfma_f32_16x16x32_bf16 v[16:19], v[128:131], v[92:95], v[16:19]
	v_mfma_f32_16x16x32_bf16 v[44:47], v[132:135], v[92:95], v[44:47]
	v_mfma_f32_16x16x32_bf16 v[56:59], v[128:131], v[116:119], v[56:59]
	v_mfma_f32_16x16x32_bf16 v[52:55], v[128:131], v[120:123], v[52:55]
	v_mfma_f32_16x16x32_bf16 v[40:43], v[132:135], v[116:119], v[40:43]
	v_mfma_f32_16x16x32_bf16 v[60:63], v[132:135], v[120:123], v[60:63]
	s_waitcnt vmcnt(0)
	s_barrier
	s_add_i32 s59, s59, -1
	s_cmp_lg_u32 s59, 0
	s_cbranch_scc1 .Lg2_loop
	s_nop 7
	s_nop 7
	s_movk_i32 s4, 0x3a00
	s_add_i32 s6, s6, s92
	v_add_u32_e32 v68, s3, v111
	s_ashr_i32 s3, s2, 31
	v_lshl_add_u64 v[64:65], s[2:3], 2, v[100:101]
	v_mad_i64_i32 v[66:67], s[2:3], v68, s4, v[64:65]
	global_store_dword v[66:67], v36, off sc0 sc1
	global_store_dword v[66:67], v32, off offset:64 sc0 sc1
	global_store_dword v[66:67], v28, off offset:128 sc0 sc1
	global_store_dword v[66:67], v24, off offset:192 sc0 sc1
	v_or_b32_e32 v24, 1, v68
	v_mad_i64_i32 v[66:67], s[2:3], v24, s4, v[64:65]
	v_or_b32_e32 v24, 2, v68
	global_store_dword v[66:67], v37, off sc0 sc1
	global_store_dword v[66:67], v33, off offset:64 sc0 sc1
	global_store_dword v[66:67], v29, off offset:128 sc0 sc1
	global_store_dword v[66:67], v25, off offset:192 sc0 sc1
	v_mad_i64_i32 v[24:25], s[2:3], v24, s4, v[64:65]
	global_store_dword v[24:25], v38, off sc0 sc1
	global_store_dword v[24:25], v34, off offset:64 sc0 sc1
	global_store_dword v[24:25], v30, off offset:128 sc0 sc1
	global_store_dword v[24:25], v26, off offset:192 sc0 sc1
	v_or_b32_e32 v24, 3, v68
	v_mad_i64_i32 v[24:25], s[2:3], v24, s4, v[64:65]
	global_store_dword v[24:25], v39, off sc0 sc1
	global_store_dword v[24:25], v35, off offset:64 sc0 sc1
	global_store_dword v[24:25], v31, off offset:128 sc0 sc1
	global_store_dword v[24:25], v27, off offset:192 sc0 sc1
	v_or_b32_e32 v24, 16, v68
	v_mad_i64_i32 v[24:25], s[2:3], v24, s4, v[64:65]
	global_store_dword v[24:25], v8, off sc0 sc1
	global_store_dword v[24:25], v4, off offset:64 sc0 sc1
	global_store_dword v[24:25], v0, off offset:128 sc0 sc1
	global_store_dword v[24:25], v20, off offset:192 sc0 sc1
	v_or_b32_e32 v0, 17, v68
	v_mad_i64_i32 v[24:25], s[2:3], v0, s4, v[64:65]
	v_or_b32_e32 v0, 18, v68
	global_store_dword v[24:25], v9, off sc0 sc1
	global_store_dword v[24:25], v5, off offset:64 sc0 sc1
	global_store_dword v[24:25], v1, off offset:128 sc0 sc1
	global_store_dword v[24:25], v21, off offset:192 sc0 sc1
	v_mad_i64_i32 v[0:1], s[2:3], v0, s4, v[64:65]
	global_store_dword v[0:1], v10, off sc0 sc1
	global_store_dword v[0:1], v6, off offset:64 sc0 sc1
	global_store_dword v[0:1], v2, off offset:128 sc0 sc1
	global_store_dword v[0:1], v22, off offset:192 sc0 sc1
	v_or_b32_e32 v0, 19, v68
	v_mad_i64_i32 v[0:1], s[2:3], v0, s4, v[64:65]
	global_store_dword v[0:1], v11, off sc0 sc1
	global_store_dword v[0:1], v7, off offset:64 sc0 sc1
	global_store_dword v[0:1], v3, off offset:128 sc0 sc1
	global_store_dword v[0:1], v23, off offset:192 sc0 sc1
	v_or_b32_e32 v0, 32, v68
	v_mad_i64_i32 v[0:1], s[2:3], v0, s4, v[64:65]
	global_store_dword v[0:1], v12, off sc0 sc1
	global_store_dword v[0:1], v16, off offset:64 sc0 sc1
	global_store_dword v[0:1], v56, off offset:128 sc0 sc1
	global_store_dword v[0:1], v52, off offset:192 sc0 sc1
	v_or_b32_e32 v0, 33, v68
	v_mad_i64_i32 v[0:1], s[2:3], v0, s4, v[64:65]
	global_store_dword v[0:1], v13, off sc0 sc1
	global_store_dword v[0:1], v17, off offset:64 sc0 sc1
	global_store_dword v[0:1], v57, off offset:128 sc0 sc1
	global_store_dword v[0:1], v53, off offset:192 sc0 sc1
	v_or_b32_e32 v0, 34, v68
	v_mad_i64_i32 v[0:1], s[2:3], v0, s4, v[64:65]
	global_store_dword v[0:1], v14, off sc0 sc1
	global_store_dword v[0:1], v18, off offset:64 sc0 sc1
	global_store_dword v[0:1], v58, off offset:128 sc0 sc1
	global_store_dword v[0:1], v54, off offset:192 sc0 sc1
	v_or_b32_e32 v0, 35, v68
	v_mad_i64_i32 v[0:1], s[2:3], v0, s4, v[64:65]
	global_store_dword v[0:1], v15, off sc0 sc1
	global_store_dword v[0:1], v19, off offset:64 sc0 sc1
	global_store_dword v[0:1], v59, off offset:128 sc0 sc1
	global_store_dword v[0:1], v55, off offset:192 sc0 sc1
	v_or_b32_e32 v0, 48, v68
	v_mad_i64_i32 v[0:1], s[2:3], v0, s4, v[64:65]
	global_store_dword v[0:1], v48, off sc0 sc1
	global_store_dword v[0:1], v44, off offset:64 sc0 sc1
	global_store_dword v[0:1], v40, off offset:128 sc0 sc1
	s_nop 4
	global_store_dword v[0:1], v60, off offset:192 sc0 sc1
	v_or_b32_e32 v0, 49, v68
	v_mad_i64_i32 v[0:1], s[2:3], v0, s4, v[64:65]
	global_store_dword v[0:1], v49, off sc0 sc1
	global_store_dword v[0:1], v45, off offset:64 sc0 sc1
	global_store_dword v[0:1], v41, off offset:128 sc0 sc1
	global_store_dword v[0:1], v61, off offset:192 sc0 sc1
	v_or_b32_e32 v0, 50, v68
	v_mad_i64_i32 v[0:1], s[2:3], v0, s4, v[64:65]
	global_store_dword v[0:1], v50, off sc0 sc1
	global_store_dword v[0:1], v46, off offset:64 sc0 sc1
	global_store_dword v[0:1], v42, off offset:128 sc0 sc1
	global_store_dword v[0:1], v62, off offset:192 sc0 sc1
	v_or_b32_e32 v0, 51, v68
	v_mad_i64_i32 v[0:1], s[2:3], v0, s4, v[64:65]
	s_cmp_ge_i32 s6, s21
	global_store_dword v[0:1], v51, off sc0 sc1
	global_store_dword v[0:1], v47, off offset:64 sc0 sc1
	global_store_dword v[0:1], v43, off offset:128 sc0 sc1
	global_store_dword v[0:1], v63, off offset:192 sc0 sc1
	s_cbranch_scc0 .LBB0_259
